# v48: v46 + the two waits at the end of each load segment merged into one s_waitcnt vmcnt(N) lgkmcnt(0) (17 sites)
# baseline (speedup 1.0000x reference)
.Lrb_skip_230:
.LBB0_230:
	s_add_u32 s98, s0, 0xfff00000
	s_addc_u32 s99, s1, -1
	s_add_u32 s28, s0, 0xfff00080
	s_addc_u32 s29, s1, -1
	s_add_i32 s51, 0, 0x10000
	s_cmp_eq_u32 s50, 60
	s_cselect_b32 s31, s34, s29
	s_cselect_b32 s30, s35, s28
	v_add_u32_e32 v0, s51, v179
	s_cselect_b32 s29, s27, s43
	s_cselect_b32 s28, s40, s41
	s_add_i32 s77, 0, 0x14000
	ds_read_b128 v[130:133], v0
	ds_read_b128 v[134:137], v0 offset:1024
	ds_read_b128 v[138:141], v0 offset:2048
	ds_read_b128 v[142:145], v0 offset:3072
	v_add_u32_e32 v0, s77, v179
	ds_read_b128 v[146:149], v0
	ds_read_b128 v[150:153], v0 offset:1024
	ds_read_b128 v[154:157], v0 offset:2048
	ds_read_b128 v[158:161], v0 offset:3072
	s_mov_b32 m0, s54
	ds_read_b128 v[174:177], v192
	ds_read_b128 v[180:183], v192 offset:1024
	ds_read_b128 v[184:187], v192 offset:2048
	ds_read_b128 v[188:191], v192 offset:3072
	ds_read_b128 v[200:203], v192 offset:4096
	ds_read_b128 v[204:207], v192 offset:5120
	ds_read_b128 v[208:211], v192 offset:6144
	ds_read_b128 v[212:215], v192 offset:7168
	global_load_lds_dwordx4 v168, s[98:99]
	s_mov_b32 m0, s55
	s_nop 0
	global_load_lds_dwordx4 v164, s[98:99]
	s_add_i32 m0, s14, 0xc000
	s_nop 0
	global_load_lds_dwordx4 v170, s[0:1]
	s_add_i32 m0, s14, 0xe000
	s_nop 0
	global_load_lds_dwordx4 v172, s[0:1]
	s_waitcnt vmcnt(8) lgkmcnt(0)
	s_barrier
	v_mfma_f32_16x16x32_bf16 v[126:129], v[130:133], v[174:177], v[126:129]
	v_mfma_f32_16x16x32_bf16 v[126:129], v[134:137], v[180:183], v[126:129]
	v_mfma_f32_16x16x32_bf16 v[110:113], v[130:133], v[184:187], v[110:113]
	v_mfma_f32_16x16x32_bf16 v[110:113], v[134:137], v[188:191], v[110:113]
	v_mfma_f32_16x16x32_bf16 v[94:97], v[130:133], v[200:203], v[94:97]
	v_mfma_f32_16x16x32_bf16 v[94:97], v[134:137], v[204:207], v[94:97]
	v_mfma_f32_16x16x32_bf16 v[78:81], v[130:133], v[208:211], v[78:81]
	v_mfma_f32_16x16x32_bf16 v[78:81], v[134:137], v[212:215], v[78:81]
	v_mfma_f32_16x16x32_bf16 v[122:125], v[138:141], v[174:177], v[122:125]
	v_mfma_f32_16x16x32_bf16 v[122:125], v[142:145], v[180:183], v[122:125]
	v_mfma_f32_16x16x32_bf16 v[106:109], v[138:141], v[184:187], v[106:109]
	v_mfma_f32_16x16x32_bf16 v[106:109], v[142:145], v[188:191], v[106:109]
	v_mfma_f32_16x16x32_bf16 v[90:93], v[138:141], v[200:203], v[90:93]
	v_mfma_f32_16x16x32_bf16 v[90:93], v[142:145], v[204:207], v[90:93]
	v_mfma_f32_16x16x32_bf16 v[74:77], v[138:141], v[208:211], v[74:77]
	v_mfma_f32_16x16x32_bf16 v[74:77], v[142:145], v[212:215], v[74:77]
	v_mfma_f32_16x16x32_bf16 v[118:121], v[146:149], v[174:177], v[118:121]
	v_mfma_f32_16x16x32_bf16 v[118:121], v[150:153], v[180:183], v[118:121]
	v_mfma_f32_16x16x32_bf16 v[102:105], v[146:149], v[184:187], v[102:105]
	v_mfma_f32_16x16x32_bf16 v[102:105], v[150:153], v[188:191], v[102:105]
	v_mfma_f32_16x16x32_bf16 v[86:89], v[146:149], v[200:203], v[86:89]
	v_mfma_f32_16x16x32_bf16 v[86:89], v[150:153], v[204:207], v[86:89]
	v_mfma_f32_16x16x32_bf16 v[70:73], v[146:149], v[208:211], v[70:73]
	v_mfma_f32_16x16x32_bf16 v[70:73], v[150:153], v[212:215], v[70:73]
	v_mfma_f32_16x16x32_bf16 v[114:117], v[154:157], v[174:177], v[114:117]
	v_mfma_f32_16x16x32_bf16 v[114:117], v[158:161], v[180:183], v[114:117]
	v_mfma_f32_16x16x32_bf16 v[98:101], v[154:157], v[184:187], v[98:101]
	v_mfma_f32_16x16x32_bf16 v[98:101], v[158:161], v[188:191], v[98:101]
	v_mfma_f32_16x16x32_bf16 v[82:85], v[154:157], v[200:203], v[82:85]
	v_mfma_f32_16x16x32_bf16 v[82:85], v[158:161], v[204:207], v[82:85]
	v_mfma_f32_16x16x32_bf16 v[66:69], v[154:157], v[208:211], v[66:69]
	v_mfma_f32_16x16x32_bf16 v[66:69], v[158:161], v[212:215], v[66:69]
	s_barrier
	s_add_i32 s51, s51, s9
	s_mov_b32 m0, s51
	ds_read_b128 v[174:177], v192 offset:16384
	ds_read_b128 v[180:183], v192 offset:17408
	ds_read_b128 v[184:187], v192 offset:18432
	ds_read_b128 v[188:191], v192 offset:19456
	ds_read_b128 v[200:203], v192 offset:20480
	ds_read_b128 v[204:207], v192 offset:21504
	ds_read_b128 v[208:211], v192 offset:22528
	ds_read_b128 v[212:215], v192 offset:23552
	global_load_lds_dwordx4 v166, s[28:29]
	s_add_i32 m0, s51, 0x2000
	s_add_u32 s80, s28, 0x100000
	s_addc_u32 s81, s29, 0
	s_add_i32 s51, s77, s9
	global_load_lds_dwordx4 v162, s[28:29]
	s_mov_b32 m0, s51
	s_nop 0
	global_load_lds_dwordx4 v166, s[80:81]
	s_add_i32 m0, s51, 0x2000
	s_nop 0
	global_load_lds_dwordx4 v162, s[80:81]
	s_waitcnt vmcnt(6) lgkmcnt(0)
	s_barrier
	v_mfma_f32_16x16x32_bf16 v[62:65], v[130:133], v[174:177], v[62:65]
	v_mfma_f32_16x16x32_bf16 v[62:65], v[134:137], v[180:183], v[62:65]
	v_mfma_f32_16x16x32_bf16 v[46:49], v[130:133], v[184:187], v[46:49]
	v_mfma_f32_16x16x32_bf16 v[46:49], v[134:137], v[188:191], v[46:49]
	v_mfma_f32_16x16x32_bf16 v[30:33], v[130:133], v[200:203], v[30:33]
	v_mfma_f32_16x16x32_bf16 v[30:33], v[134:137], v[204:207], v[30:33]
	v_mfma_f32_16x16x32_bf16 v[14:17], v[130:133], v[208:211], v[14:17]
	v_mfma_f32_16x16x32_bf16 v[14:17], v[134:137], v[212:215], v[14:17]
	v_mfma_f32_16x16x32_bf16 v[58:61], v[138:141], v[174:177], v[58:61]
	v_mfma_f32_16x16x32_bf16 v[58:61], v[142:145], v[180:183], v[58:61]
	v_mfma_f32_16x16x32_bf16 v[42:45], v[138:141], v[184:187], v[42:45]
	v_mfma_f32_16x16x32_bf16 v[42:45], v[142:145], v[188:191], v[42:45]
	v_mfma_f32_16x16x32_bf16 v[26:29], v[138:141], v[200:203], v[26:29]
	v_mfma_f32_16x16x32_bf16 v[26:29], v[142:145], v[204:207], v[26:29]
	v_mfma_f32_16x16x32_bf16 v[10:13], v[138:141], v[208:211], v[10:13]
	v_mfma_f32_16x16x32_bf16 v[10:13], v[142:145], v[212:215], v[10:13]
	v_mfma_f32_16x16x32_bf16 v[54:57], v[146:149], v[174:177], v[54:57]
	v_mfma_f32_16x16x32_bf16 v[54:57], v[150:153], v[180:183], v[54:57]
	v_mfma_f32_16x16x32_bf16 v[38:41], v[146:149], v[184:187], v[38:41]
	v_mfma_f32_16x16x32_bf16 v[38:41], v[150:153], v[188:191], v[38:41]
	v_mfma_f32_16x16x32_bf16 v[22:25], v[146:149], v[200:203], v[22:25]
	v_mfma_f32_16x16x32_bf16 v[22:25], v[150:153], v[204:207], v[22:25]
	v_mfma_f32_16x16x32_bf16 v[6:9], v[146:149], v[208:211], v[6:9]
	v_mfma_f32_16x16x32_bf16 v[6:9], v[150:153], v[212:215], v[6:9]
	v_mfma_f32_16x16x32_bf16 v[50:53], v[154:157], v[174:177], v[50:53]
	v_mfma_f32_16x16x32_bf16 v[50:53], v[158:161], v[180:183], v[50:53]
	v_mfma_f32_16x16x32_bf16 v[34:37], v[154:157], v[184:187], v[34:37]
	v_mfma_f32_16x16x32_bf16 v[34:37], v[158:161], v[188:191], v[34:37]
	v_mfma_f32_16x16x32_bf16 v[18:21], v[154:157], v[200:203], v[18:21]
	v_mfma_f32_16x16x32_bf16 v[18:21], v[158:161], v[204:207], v[18:21]
	v_mfma_f32_16x16x32_bf16 v[2:5], v[154:157], v[208:211], v[2:5]
	v_mfma_f32_16x16x32_bf16 v[2:5], v[158:161], v[212:215], v[2:5]
	s_barrier
	s_add_i32 s51, 0, 0x18000
	v_add_u32_e32 v0, s51, v179
	s_add_i32 s77, 0, 0x1c000
	ds_read_b128 v[130:133], v0
	ds_read_b128 v[134:137], v0 offset:1024
	ds_read_b128 v[138:141], v0 offset:2048
	ds_read_b128 v[142:145], v0 offset:3072
	v_add_u32_e32 v0, s77, v179
	ds_read_b128 v[146:149], v0
	ds_read_b128 v[150:153], v0 offset:1024
	ds_read_b128 v[154:157], v0 offset:2048
	ds_read_b128 v[158:161], v0 offset:3072
	s_mov_b32 m0, s14
	ds_read_b128 v[174:177], v192 offset:32768
	ds_read_b128 v[180:183], v192 offset:33792
	ds_read_b128 v[184:187], v192 offset:34816
	ds_read_b128 v[188:191], v192 offset:35840
	ds_read_b128 v[200:203], v192 offset:36864
	ds_read_b128 v[204:207], v192 offset:37888
	ds_read_b128 v[208:211], v192 offset:38912
	ds_read_b128 v[212:215], v192 offset:39936
	global_load_lds_dwordx4 v168, s[30:31]
	s_mov_b32 m0, s15
	s_nop 0
	global_load_lds_dwordx4 v164, s[30:31]
	s_add_u32 s30, s30, 0x100000
	s_addc_u32 s31, s31, 0
	s_mov_b32 m0, s52
	s_nop 0
	global_load_lds_dwordx4 v168, s[30:31]
	s_mov_b32 m0, s53
	s_nop 0
	global_load_lds_dwordx4 v164, s[30:31]
	s_waitcnt vmcnt(8) lgkmcnt(0)
	s_barrier
	v_mfma_f32_16x16x32_bf16 v[126:129], v[130:133], v[174:177], v[126:129]
	v_mfma_f32_16x16x32_bf16 v[126:129], v[134:137], v[180:183], v[126:129]
	v_mfma_f32_16x16x32_bf16 v[110:113], v[130:133], v[184:187], v[110:113]
	v_mfma_f32_16x16x32_bf16 v[110:113], v[134:137], v[188:191], v[110:113]
	v_mfma_f32_16x16x32_bf16 v[94:97], v[130:133], v[200:203], v[94:97]
	v_mfma_f32_16x16x32_bf16 v[94:97], v[134:137], v[204:207], v[94:97]
	v_mfma_f32_16x16x32_bf16 v[78:81], v[130:133], v[208:211], v[78:81]
	v_mfma_f32_16x16x32_bf16 v[78:81], v[134:137], v[212:215], v[78:81]
	v_mfma_f32_16x16x32_bf16 v[122:125], v[138:141], v[174:177], v[122:125]
	v_mfma_f32_16x16x32_bf16 v[122:125], v[142:145], v[180:183], v[122:125]
	v_mfma_f32_16x16x32_bf16 v[106:109], v[138:141], v[184:187], v[106:109]
	v_mfma_f32_16x16x32_bf16 v[106:109], v[142:145], v[188:191], v[106:109]
	v_mfma_f32_16x16x32_bf16 v[90:93], v[138:141], v[200:203], v[90:93]
	v_mfma_f32_16x16x32_bf16 v[90:93], v[142:145], v[204:207], v[90:93]
	v_mfma_f32_16x16x32_bf16 v[74:77], v[138:141], v[208:211], v[74:77]
	v_mfma_f32_16x16x32_bf16 v[74:77], v[142:145], v[212:215], v[74:77]
	v_mfma_f32_16x16x32_bf16 v[118:121], v[146:149], v[174:177], v[118:121]
	v_mfma_f32_16x16x32_bf16 v[118:121], v[150:153], v[180:183], v[118:121]
	v_mfma_f32_16x16x32_bf16 v[102:105], v[146:149], v[184:187], v[102:105]
	v_mfma_f32_16x16x32_bf16 v[102:105], v[150:153], v[188:191], v[102:105]
	v_mfma_f32_16x16x32_bf16 v[86:89], v[146:149], v[200:203], v[86:89]
	v_mfma_f32_16x16x32_bf16 v[86:89], v[150:153], v[204:207], v[86:89]
	v_mfma_f32_16x16x32_bf16 v[70:73], v[146:149], v[208:211], v[70:73]
	v_mfma_f32_16x16x32_bf16 v[70:73], v[150:153], v[212:215], v[70:73]
	v_mfma_f32_16x16x32_bf16 v[114:117], v[154:157], v[174:177], v[114:117]
	v_mfma_f32_16x16x32_bf16 v[114:117], v[158:161], v[180:183], v[114:117]
	v_mfma_f32_16x16x32_bf16 v[98:101], v[154:157], v[184:187], v[98:101]
	v_mfma_f32_16x16x32_bf16 v[98:101], v[158:161], v[188:191], v[98:101]
	v_mfma_f32_16x16x32_bf16 v[82:85], v[154:157], v[200:203], v[82:85]
	v_mfma_f32_16x16x32_bf16 v[82:85], v[158:161], v[204:207], v[82:85]
	v_mfma_f32_16x16x32_bf16 v[66:69], v[154:157], v[208:211], v[66:69]
	v_mfma_f32_16x16x32_bf16 v[66:69], v[158:161], v[212:215], v[66:69]
	s_barrier
	s_add_u32 s98, s28, 0x80
	s_addc_u32 s99, s29, 0
	s_add_i32 s30, s51, s9
	s_mov_b32 m0, s30
	ds_read_b128 v[174:177], v192 offset:49152
	ds_read_b128 v[180:183], v192 offset:50176
	ds_read_b128 v[184:187], v192 offset:51200
	ds_read_b128 v[188:191], v192 offset:52224
	ds_read_b128 v[200:203], v192 offset:53248
	ds_read_b128 v[204:207], v192 offset:54272
	ds_read_b128 v[208:211], v192 offset:55296
	ds_read_b128 v[212:215], v192 offset:56320
	global_load_lds_dwordx4 v166, s[98:99]
	s_add_i32 m0, s30, 0x2000
	s_add_u32 s28, s28, 0x100080
	s_addc_u32 s29, s29, 0
	s_add_i32 s30, s77, s9
	global_load_lds_dwordx4 v162, s[98:99]
	s_mov_b32 m0, s30
	s_nop 0
	global_load_lds_dwordx4 v166, s[28:29]
	s_add_i32 m0, s30, 0x2000
	s_nop 0
	global_load_lds_dwordx4 v162, s[28:29]
	s_waitcnt vmcnt(6) lgkmcnt(0)
	s_barrier
	v_mfma_f32_16x16x32_bf16 v[62:65], v[130:133], v[174:177], v[62:65]
	v_mfma_f32_16x16x32_bf16 v[62:65], v[134:137], v[180:183], v[62:65]
	v_mfma_f32_16x16x32_bf16 v[46:49], v[130:133], v[184:187], v[46:49]
	v_mfma_f32_16x16x32_bf16 v[46:49], v[134:137], v[188:191], v[46:49]
	v_mfma_f32_16x16x32_bf16 v[30:33], v[130:133], v[200:203], v[30:33]
	v_mfma_f32_16x16x32_bf16 v[30:33], v[134:137], v[204:207], v[30:33]
	v_mfma_f32_16x16x32_bf16 v[14:17], v[130:133], v[208:211], v[14:17]
	v_mfma_f32_16x16x32_bf16 v[14:17], v[134:137], v[212:215], v[14:17]
	v_mfma_f32_16x16x32_bf16 v[58:61], v[138:141], v[174:177], v[58:61]
	v_mfma_f32_16x16x32_bf16 v[58:61], v[142:145], v[180:183], v[58:61]
	v_mfma_f32_16x16x32_bf16 v[42:45], v[138:141], v[184:187], v[42:45]
	v_mfma_f32_16x16x32_bf16 v[42:45], v[142:145], v[188:191], v[42:45]
	v_mfma_f32_16x16x32_bf16 v[26:29], v[138:141], v[200:203], v[26:29]
	v_mfma_f32_16x16x32_bf16 v[26:29], v[142:145], v[204:207], v[26:29]
	v_mfma_f32_16x16x32_bf16 v[10:13], v[138:141], v[208:211], v[10:13]
	v_mfma_f32_16x16x32_bf16 v[10:13], v[142:145], v[212:215], v[10:13]
	v_mfma_f32_16x16x32_bf16 v[54:57], v[146:149], v[174:177], v[54:57]
	v_mfma_f32_16x16x32_bf16 v[54:57], v[150:153], v[180:183], v[54:57]
	v_mfma_f32_16x16x32_bf16 v[38:41], v[146:149], v[184:187], v[38:41]
	v_mfma_f32_16x16x32_bf16 v[38:41], v[150:153], v[188:191], v[38:41]
	v_mfma_f32_16x16x32_bf16 v[22:25], v[146:149], v[200:203], v[22:25]
	v_mfma_f32_16x16x32_bf16 v[22:25], v[150:153], v[204:207], v[22:25]
	v_mfma_f32_16x16x32_bf16 v[6:9], v[146:149], v[208:211], v[6:9]
	v_mfma_f32_16x16x32_bf16 v[6:9], v[150:153], v[212:215], v[6:9]
	v_mfma_f32_16x16x32_bf16 v[50:53], v[154:157], v[174:177], v[50:53]
	v_mfma_f32_16x16x32_bf16 v[50:53], v[158:161], v[180:183], v[50:53]
	v_mfma_f32_16x16x32_bf16 v[34:37], v[154:157], v[184:187], v[34:37]
	v_mfma_f32_16x16x32_bf16 v[34:37], v[158:161], v[188:191], v[34:37]
	v_mfma_f32_16x16x32_bf16 v[18:21], v[154:157], v[200:203], v[18:21]
	v_mfma_f32_16x16x32_bf16 v[18:21], v[158:161], v[204:207], v[18:21]
	v_mfma_f32_16x16x32_bf16 v[2:5], v[154:157], v[208:211], v[2:5]
	v_mfma_f32_16x16x32_bf16 v[2:5], v[158:161], v[212:215], v[2:5]
	s_barrier
	s_add_i32 s50, s50, 2
	s_add_u32 s0, s0, 0x100
	s_addc_u32 s1, s1, 0
	s_add_u32 s41, s41, 0x100
	s_addc_u32 s43, s43, 0
	s_cmp_gt_u32 s50, 61
	s_cbranch_scc0 .LBB0_230
	s_and_b64 vcc, exec, s[22:23]
	s_cbranch_vccz .LBB0_233
	s_barrier

.Lspf_j2:
	s_waitcnt lgkmcnt(0)
	s_barrier
	v_mfma_i32_16x16x64_i8 v[142:145], v[34:37], v[174:177], v[142:145]
	v_mfma_i32_16x16x64_i8 v[142:145], v[38:41], v[178:181], v[142:145]
	v_mfma_i32_16x16x64_i8 v[134:137], v[34:37], v[182:185], v[134:137]
	v_mfma_i32_16x16x64_i8 v[134:137], v[38:41], v[186:189], v[134:137]
	v_mfma_i32_16x16x64_i8 v[122:125], v[34:37], v[190:193], v[122:125]
	v_mfma_i32_16x16x64_i8 v[122:125], v[38:41], v[200:203], v[122:125]
	v_mfma_i32_16x16x64_i8 v[106:109], v[34:37], v[204:207], v[106:109]
	v_mfma_i32_16x16x64_i8 v[106:109], v[38:41], v[208:211], v[106:109]
	v_mfma_i32_16x16x64_i8 v[138:141], v[58:61], v[174:177], v[138:141]
	v_mfma_i32_16x16x64_i8 v[138:141], v[62:65], v[178:181], v[138:141]
	v_mfma_i32_16x16x64_i8 v[130:133], v[58:61], v[182:185], v[130:133]
	v_mfma_i32_16x16x64_i8 v[130:133], v[62:65], v[186:189], v[130:133]
	v_mfma_i32_16x16x64_i8 v[114:117], v[58:61], v[190:193], v[114:117]
	v_mfma_i32_16x16x64_i8 v[114:117], v[62:65], v[200:203], v[114:117]
	v_mfma_i32_16x16x64_i8 v[98:101], v[58:61], v[204:207], v[98:101]
	v_mfma_i32_16x16x64_i8 v[98:101], v[62:65], v[208:211], v[98:101]
	v_mfma_i32_16x16x64_i8 v[126:129], v[146:149], v[174:177], v[126:129]
	v_mfma_i32_16x16x64_i8 v[126:129], v[150:153], v[178:181], v[126:129]
	v_mfma_i32_16x16x64_i8 v[110:113], v[146:149], v[182:185], v[110:113]
	v_mfma_i32_16x16x64_i8 v[110:113], v[150:153], v[186:189], v[110:113]
	v_mfma_i32_16x16x64_i8 v[94:97], v[146:149], v[190:193], v[94:97]
	v_mfma_i32_16x16x64_i8 v[94:97], v[150:153], v[200:203], v[94:97]
	v_mfma_i32_16x16x64_i8 v[86:89], v[146:149], v[204:207], v[86:89]
	v_mfma_i32_16x16x64_i8 v[86:89], v[150:153], v[208:211], v[86:89]
	v_mfma_i32_16x16x64_i8 v[118:121], v[154:157], v[174:177], v[118:121]
	v_mfma_i32_16x16x64_i8 v[118:121], v[158:161], v[178:181], v[118:121]
	v_mfma_i32_16x16x64_i8 v[102:105], v[154:157], v[182:185], v[102:105]
	v_mfma_i32_16x16x64_i8 v[102:105], v[158:161], v[186:189], v[102:105]
	v_mfma_i32_16x16x64_i8 v[90:93], v[154:157], v[190:193], v[90:93]
	v_mfma_i32_16x16x64_i8 v[90:93], v[158:161], v[200:203], v[90:93]
	v_mfma_i32_16x16x64_i8 v[82:85], v[154:157], v[204:207], v[82:85]
	v_mfma_i32_16x16x64_i8 v[82:85], v[158:161], v[208:211], v[82:85]
	s_barrier
	s_add_i32 s30, s42, s81
	s_add_u32 s98, s28, 0x80
	s_addc_u32 s99, s29, 0
	s_mov_b32 m0, s30
	ds_read_b128 v[174:177], v250 offset:49152
	ds_read_b128 v[178:181], v250 offset:50176
	ds_read_b128 v[182:185], v250 offset:51200
	ds_read_b128 v[186:189], v250 offset:52224
	ds_read_b128 v[190:193], v250 offset:53248
	ds_read_b128 v[200:203], v250 offset:54272
	ds_read_b128 v[204:207], v250 offset:55296
	ds_read_b128 v[208:211], v250 offset:56320
	global_load_lds_dwordx4 v164, s[98:99]
	s_add_i32 m0, s30, 0x2000
	s_add_u32 s28, s28, 0x80080
	s_addc_u32 s29, s29, 0
	s_add_i32 s30, s43, s81
	global_load_lds_dwordx4 v168, s[98:99]
	s_mov_b32 m0, s30
	s_nop 0
	global_load_lds_dwordx4 v164, s[28:29]
	s_add_i32 m0, s30, 0x2000
	s_nop 0
	global_load_lds_dwordx4 v168, s[28:29]
	s_waitcnt vmcnt(6) lgkmcnt(0)
	s_barrier
	v_mfma_i32_16x16x64_i8 v[78:81], v[34:37], v[174:177], v[78:81]
	v_mfma_i32_16x16x64_i8 v[78:81], v[38:41], v[178:181], v[78:81]
	v_mfma_i32_16x16x64_i8 v[70:73], v[34:37], v[182:185], v[70:73]
	v_mfma_i32_16x16x64_i8 v[70:73], v[38:41], v[186:189], v[70:73]
	v_mfma_i32_16x16x64_i8 v[54:57], v[34:37], v[190:193], v[54:57]
	v_mfma_i32_16x16x64_i8 v[54:57], v[38:41], v[200:203], v[54:57]
	v_mfma_i32_16x16x64_i8 v[2:5], v[34:37], v[204:207], v[2:5]
	v_mfma_i32_16x16x64_i8 v[38:41], v[38:41], v[208:211], v[2:5]
	v_mfma_i32_16x16x64_i8 v[74:77], v[58:61], v[174:177], v[74:77]
	v_mfma_i32_16x16x64_i8 v[74:77], v[62:65], v[178:181], v[74:77]
	v_mfma_i32_16x16x64_i8 v[66:69], v[58:61], v[182:185], v[66:69]
	v_mfma_i32_16x16x64_i8 v[66:69], v[62:65], v[186:189], v[66:69]
	v_mfma_i32_16x16x64_i8 v[50:53], v[58:61], v[190:193], v[50:53]
	v_mfma_i32_16x16x64_i8 v[50:53], v[62:65], v[200:203], v[50:53]
	v_mfma_i32_16x16x64_i8 v[2:5], v[58:61], v[204:207], v[6:9]
	v_mfma_i32_16x16x64_i8 v[34:37], v[62:65], v[208:211], v[2:5]
	v_mfma_i32_16x16x64_i8 v[2:5], v[146:149], v[174:177], v[10:13]
	v_mfma_i32_16x16x64_i8 v[62:65], v[150:153], v[178:181], v[2:5]
	v_mfma_i32_16x16x64_i8 v[2:5], v[154:157], v[174:177], v[14:17]
	v_mfma_i32_16x16x64_i8 v[58:61], v[158:161], v[178:181], v[2:5]
	v_mfma_i32_16x16x64_i8 v[2:5], v[146:149], v[182:185], v[46:49]
	v_mfma_i32_16x16x64_i8 v[46:49], v[150:153], v[186:189], v[2:5]
	v_mfma_i32_16x16x64_i8 v[2:5], v[154:157], v[182:185], v[42:45]
	v_mfma_i32_16x16x64_i8 v[42:45], v[158:161], v[186:189], v[2:5]
	v_mfma_i32_16x16x64_i8 v[2:5], v[146:149], v[190:193], v[30:33]
	v_mfma_i32_16x16x64_i8 v[30:33], v[150:153], v[200:203], v[2:5]
	v_mfma_i32_16x16x64_i8 v[2:5], v[154:157], v[190:193], v[26:29]
	v_mfma_i32_16x16x64_i8 v[26:29], v[158:161], v[200:203], v[2:5]
	v_mfma_i32_16x16x64_i8 v[2:5], v[146:149], v[204:207], v[22:25]
	v_mfma_i32_16x16x64_i8 v[22:25], v[150:153], v[208:211], v[2:5]
	v_mfma_i32_16x16x64_i8 v[2:5], v[154:157], v[204:207], v[18:21]
	v_mfma_i32_16x16x64_i8 v[18:21], v[158:161], v[208:211], v[2:5]
	s_barrier
	s_add_i32 s41, s41, 2
	s_add_u32 s0, s0, 0x100
	s_addc_u32 s1, s1, 0
	s_add_u32 s35, s35, 0x100
	s_addc_u32 s40, s40, 0
	s_cmp_gt_u32 s41, 29
	s_cbranch_scc0 .LBB0_300

.Lrb_skip_577:
.LBB0_577:
	s_add_u32 s98, s30, 0xfff80000
	s_addc_u32 s99, s31, -1
	s_add_u32 s34, s30, 0xfff80080
	s_addc_u32 s35, s31, -1
	s_add_i32 s66, 0, 0x10000
	s_cmp_eq_u32 s57, 28
	s_cselect_b32 s43, s19, s35
	s_cselect_b32 s42, s23, s34
	v_add_u32_e32 v0, s66, v228
	s_cselect_b32 s35, s25, s56
	s_cselect_b32 s34, s54, s55
	s_add_i32 s73, 0, 0x14000
	ds_read_b128 v[132:135], v0
	ds_read_b128 v[136:139], v0 offset:1024
	ds_read_b128 v[140:143], v0 offset:2048
	ds_read_b128 v[144:147], v0 offset:3072
	v_add_u32_e32 v0, s73, v228
	ds_read_b128 v[148:151], v0
	ds_read_b128 v[152:155], v0 offset:1024
	ds_read_b128 v[156:159], v0 offset:2048
	ds_read_b128 v[160:163], v0 offset:3072
	s_mov_b32 m0, s50
	ds_read_b128 v[164:167], v230
	ds_read_b128 v[168:171], v230 offset:1024
	ds_read_b128 v[172:175], v230 offset:2048
	ds_read_b128 v[176:179], v230 offset:3072
	ds_read_b128 v[180:183], v230 offset:4096
	ds_read_b128 v[184:187], v230 offset:5120
	ds_read_b128 v[188:191], v230 offset:6144
	ds_read_b128 v[192:195], v230 offset:7168
	global_load_lds_dwordx4 v206, s[98:99]
	s_mov_b32 m0, s51
	s_nop 0
	global_load_lds_dwordx4 v202, s[98:99]
	s_add_i32 m0, s46, 0xc000
	s_nop 0
	global_load_lds_dwordx4 v208, s[30:31]
	s_add_i32 m0, s46, 0xe000
	s_nop 0
	global_load_lds_dwordx4 v210, s[30:31]
	s_waitcnt vmcnt(8) lgkmcnt(0)
	s_barrier
	v_mfma_f32_16x16x32_bf16 v[128:131], v[132:135], v[164:167], v[128:131]
	v_mfma_f32_16x16x32_bf16 v[128:131], v[136:139], v[168:171], v[128:131]
	v_mfma_f32_16x16x32_bf16 v[120:123], v[132:135], v[172:175], v[120:123]
	v_mfma_f32_16x16x32_bf16 v[120:123], v[136:139], v[176:179], v[120:123]
	v_mfma_f32_16x16x32_bf16 v[112:115], v[132:135], v[180:183], v[112:115]
	v_mfma_f32_16x16x32_bf16 v[112:115], v[136:139], v[184:187], v[112:115]
	v_mfma_f32_16x16x32_bf16 v[104:107], v[132:135], v[188:191], v[104:107]
	v_mfma_f32_16x16x32_bf16 v[104:107], v[136:139], v[192:195], v[104:107]
	v_mfma_f32_16x16x32_bf16 v[124:127], v[140:143], v[164:167], v[124:127]
	v_mfma_f32_16x16x32_bf16 v[124:127], v[144:147], v[168:171], v[124:127]
	v_mfma_f32_16x16x32_bf16 v[116:119], v[140:143], v[172:175], v[116:119]
	v_mfma_f32_16x16x32_bf16 v[116:119], v[144:147], v[176:179], v[116:119]
	v_mfma_f32_16x16x32_bf16 v[108:111], v[140:143], v[180:183], v[108:111]
	v_mfma_f32_16x16x32_bf16 v[108:111], v[144:147], v[184:187], v[108:111]
	v_mfma_f32_16x16x32_bf16 v[100:103], v[140:143], v[188:191], v[100:103]
	v_mfma_f32_16x16x32_bf16 v[100:103], v[144:147], v[192:195], v[100:103]
	v_mfma_f32_16x16x32_bf16 v[96:99], v[148:151], v[164:167], v[96:99]
	v_mfma_f32_16x16x32_bf16 v[96:99], v[152:155], v[168:171], v[96:99]
	v_mfma_f32_16x16x32_bf16 v[88:91], v[148:151], v[172:175], v[88:91]
	v_mfma_f32_16x16x32_bf16 v[88:91], v[152:155], v[176:179], v[88:91]
	v_mfma_f32_16x16x32_bf16 v[80:83], v[148:151], v[180:183], v[80:83]
	v_mfma_f32_16x16x32_bf16 v[80:83], v[152:155], v[184:187], v[80:83]
	v_mfma_f32_16x16x32_bf16 v[72:75], v[148:151], v[188:191], v[72:75]
	v_mfma_f32_16x16x32_bf16 v[72:75], v[152:155], v[192:195], v[72:75]
	v_mfma_f32_16x16x32_bf16 v[92:95], v[156:159], v[164:167], v[92:95]
	v_mfma_f32_16x16x32_bf16 v[92:95], v[160:163], v[168:171], v[92:95]
	v_mfma_f32_16x16x32_bf16 v[84:87], v[156:159], v[172:175], v[84:87]
	v_mfma_f32_16x16x32_bf16 v[84:87], v[160:163], v[176:179], v[84:87]
	v_mfma_f32_16x16x32_bf16 v[76:79], v[156:159], v[180:183], v[76:79]
	v_mfma_f32_16x16x32_bf16 v[76:79], v[160:163], v[184:187], v[76:79]
	v_mfma_f32_16x16x32_bf16 v[68:71], v[156:159], v[188:191], v[68:71]
	v_mfma_f32_16x16x32_bf16 v[68:71], v[160:163], v[192:195], v[68:71]
	s_barrier
	s_add_i32 s66, s66, s15
	s_mov_b32 m0, s66
	ds_read_b128 v[164:167], v230 offset:16384
	ds_read_b128 v[168:171], v230 offset:17408
	ds_read_b128 v[172:175], v230 offset:18432
	ds_read_b128 v[176:179], v230 offset:19456
	ds_read_b128 v[180:183], v230 offset:20480
	ds_read_b128 v[184:187], v230 offset:21504
	ds_read_b128 v[188:191], v230 offset:22528
	ds_read_b128 v[192:195], v230 offset:23552
	global_load_lds_dwordx4 v204, s[34:35]
	s_add_i32 m0, s66, 0x2000
	s_add_u32 s66, s34, 0x80000
	s_addc_u32 s67, s35, 0
	s_add_i32 s73, s73, s15
	global_load_lds_dwordx4 v200, s[34:35]
	s_mov_b32 m0, s73
	s_nop 0
	global_load_lds_dwordx4 v204, s[66:67]
	s_add_i32 m0, s73, 0x2000
	s_nop 0
	global_load_lds_dwordx4 v200, s[66:67]
	s_waitcnt vmcnt(6) lgkmcnt(0)
	s_barrier
	v_mfma_f32_16x16x32_bf16 v[64:67], v[132:135], v[164:167], v[64:67]
	v_mfma_f32_16x16x32_bf16 v[64:67], v[136:139], v[168:171], v[64:67]
	v_mfma_f32_16x16x32_bf16 v[56:59], v[132:135], v[172:175], v[56:59]
	v_mfma_f32_16x16x32_bf16 v[56:59], v[136:139], v[176:179], v[56:59]
	v_mfma_f32_16x16x32_bf16 v[48:51], v[132:135], v[180:183], v[48:51]
	v_mfma_f32_16x16x32_bf16 v[48:51], v[136:139], v[184:187], v[48:51]
	v_mfma_f32_16x16x32_bf16 v[40:43], v[132:135], v[188:191], v[40:43]
	v_mfma_f32_16x16x32_bf16 v[40:43], v[136:139], v[192:195], v[40:43]
	v_mfma_f32_16x16x32_bf16 v[60:63], v[140:143], v[164:167], v[60:63]
	v_mfma_f32_16x16x32_bf16 v[60:63], v[144:147], v[168:171], v[60:63]
	v_mfma_f32_16x16x32_bf16 v[52:55], v[140:143], v[172:175], v[52:55]
	v_mfma_f32_16x16x32_bf16 v[52:55], v[144:147], v[176:179], v[52:55]
	v_mfma_f32_16x16x32_bf16 v[44:47], v[140:143], v[180:183], v[44:47]
	v_mfma_f32_16x16x32_bf16 v[44:47], v[144:147], v[184:187], v[44:47]
	v_mfma_f32_16x16x32_bf16 v[36:39], v[140:143], v[188:191], v[36:39]
	v_mfma_f32_16x16x32_bf16 v[36:39], v[144:147], v[192:195], v[36:39]
	v_mfma_f32_16x16x32_bf16 v[32:35], v[148:151], v[164:167], v[32:35]
	v_mfma_f32_16x16x32_bf16 v[32:35], v[152:155], v[168:171], v[32:35]
	v_mfma_f32_16x16x32_bf16 v[28:31], v[156:159], v[164:167], v[28:31]
	v_mfma_f32_16x16x32_bf16 v[28:31], v[160:163], v[168:171], v[28:31]
	v_mfma_f32_16x16x32_bf16 v[24:27], v[148:151], v[172:175], v[24:27]
	v_mfma_f32_16x16x32_bf16 v[24:27], v[152:155], v[176:179], v[24:27]
	v_mfma_f32_16x16x32_bf16 v[20:23], v[156:159], v[172:175], v[20:23]
	v_mfma_f32_16x16x32_bf16 v[20:23], v[160:163], v[176:179], v[20:23]
	v_mfma_f32_16x16x32_bf16 v[16:19], v[148:151], v[180:183], v[16:19]
	v_mfma_f32_16x16x32_bf16 v[16:19], v[152:155], v[184:187], v[16:19]
	v_mfma_f32_16x16x32_bf16 v[12:15], v[156:159], v[180:183], v[12:15]
	v_mfma_f32_16x16x32_bf16 v[12:15], v[160:163], v[184:187], v[12:15]
	v_mfma_f32_16x16x32_bf16 v[8:11], v[148:151], v[188:191], v[8:11]
	v_mfma_f32_16x16x32_bf16 v[8:11], v[152:155], v[192:195], v[8:11]
	v_mfma_f32_16x16x32_bf16 v[2:5], v[156:159], v[188:191], v[4:7]
	v_mfma_f32_16x16x32_bf16 v[2:5], v[160:163], v[192:195], v[2:5]
	s_barrier
	s_add_i32 s66, 0, 0x18000
	v_add_u32_e32 v0, s66, v228
	s_add_i32 s67, 0, 0x1c000
	ds_read_b128 v[132:135], v0
	ds_read_b128 v[136:139], v0 offset:1024
	ds_read_b128 v[140:143], v0 offset:2048
	ds_read_b128 v[144:147], v0 offset:3072
	v_add_u32_e32 v0, s67, v228
	ds_read_b128 v[148:151], v0
	ds_read_b128 v[152:155], v0 offset:1024
	ds_read_b128 v[156:159], v0 offset:2048
	ds_read_b128 v[160:163], v0 offset:3072
	s_mov_b32 m0, s46
	ds_read_b128 v[164:167], v230 offset:32768
	ds_read_b128 v[168:171], v230 offset:33792
	ds_read_b128 v[172:175], v230 offset:34816
	ds_read_b128 v[176:179], v230 offset:35840
	ds_read_b128 v[180:183], v230 offset:36864
	ds_read_b128 v[184:187], v230 offset:37888
	ds_read_b128 v[188:191], v230 offset:38912
	ds_read_b128 v[192:195], v230 offset:39936
	global_load_lds_dwordx4 v206, s[42:43]
	s_mov_b32 m0, s47
	s_nop 0
	global_load_lds_dwordx4 v202, s[42:43]
	s_add_u32 s42, s42, 0x80000
	s_addc_u32 s43, s43, 0
	s_mov_b32 m0, s48
	s_nop 0
	global_load_lds_dwordx4 v206, s[42:43]
	s_mov_b32 m0, s49
	s_nop 0
	global_load_lds_dwordx4 v202, s[42:43]
	s_waitcnt vmcnt(8) lgkmcnt(0)
	s_barrier
	v_mfma_f32_16x16x32_bf16 v[128:131], v[132:135], v[164:167], v[128:131]
	v_mfma_f32_16x16x32_bf16 v[128:131], v[136:139], v[168:171], v[128:131]
	v_mfma_f32_16x16x32_bf16 v[120:123], v[132:135], v[172:175], v[120:123]
	v_mfma_f32_16x16x32_bf16 v[120:123], v[136:139], v[176:179], v[120:123]
	v_mfma_f32_16x16x32_bf16 v[112:115], v[132:135], v[180:183], v[112:115]
	v_mfma_f32_16x16x32_bf16 v[112:115], v[136:139], v[184:187], v[112:115]
	v_mfma_f32_16x16x32_bf16 v[104:107], v[132:135], v[188:191], v[104:107]
	v_mfma_f32_16x16x32_bf16 v[104:107], v[136:139], v[192:195], v[104:107]
	v_mfma_f32_16x16x32_bf16 v[124:127], v[140:143], v[164:167], v[124:127]
	v_mfma_f32_16x16x32_bf16 v[124:127], v[144:147], v[168:171], v[124:127]
	v_mfma_f32_16x16x32_bf16 v[116:119], v[140:143], v[172:175], v[116:119]
	v_mfma_f32_16x16x32_bf16 v[116:119], v[144:147], v[176:179], v[116:119]
	v_mfma_f32_16x16x32_bf16 v[108:111], v[140:143], v[180:183], v[108:111]
	v_mfma_f32_16x16x32_bf16 v[108:111], v[144:147], v[184:187], v[108:111]
	v_mfma_f32_16x16x32_bf16 v[100:103], v[140:143], v[188:191], v[100:103]
	v_mfma_f32_16x16x32_bf16 v[100:103], v[144:147], v[192:195], v[100:103]
	v_mfma_f32_16x16x32_bf16 v[96:99], v[148:151], v[164:167], v[96:99]
	v_mfma_f32_16x16x32_bf16 v[96:99], v[152:155], v[168:171], v[96:99]
	v_mfma_f32_16x16x32_bf16 v[88:91], v[148:151], v[172:175], v[88:91]
	v_mfma_f32_16x16x32_bf16 v[88:91], v[152:155], v[176:179], v[88:91]
	v_mfma_f32_16x16x32_bf16 v[80:83], v[148:151], v[180:183], v[80:83]
	v_mfma_f32_16x16x32_bf16 v[80:83], v[152:155], v[184:187], v[80:83]
	v_mfma_f32_16x16x32_bf16 v[72:75], v[148:151], v[188:191], v[72:75]
	v_mfma_f32_16x16x32_bf16 v[72:75], v[152:155], v[192:195], v[72:75]
	v_mfma_f32_16x16x32_bf16 v[92:95], v[156:159], v[164:167], v[92:95]
	v_mfma_f32_16x16x32_bf16 v[92:95], v[160:163], v[168:171], v[92:95]
	v_mfma_f32_16x16x32_bf16 v[84:87], v[156:159], v[172:175], v[84:87]
	v_mfma_f32_16x16x32_bf16 v[84:87], v[160:163], v[176:179], v[84:87]
	v_mfma_f32_16x16x32_bf16 v[76:79], v[156:159], v[180:183], v[76:79]
	v_mfma_f32_16x16x32_bf16 v[76:79], v[160:163], v[184:187], v[76:79]
	v_mfma_f32_16x16x32_bf16 v[68:71], v[156:159], v[188:191], v[68:71]
	v_mfma_f32_16x16x32_bf16 v[68:71], v[160:163], v[192:195], v[68:71]
	s_barrier
	s_add_i32 s42, s66, s15
	s_add_u32 s98, s34, 0x80
	s_addc_u32 s99, s35, 0
	s_mov_b32 m0, s42
	ds_read_b128 v[164:167], v230 offset:49152
	ds_read_b128 v[168:171], v230 offset:50176
	ds_read_b128 v[172:175], v230 offset:51200
	ds_read_b128 v[176:179], v230 offset:52224
	ds_read_b128 v[180:183], v230 offset:53248
	ds_read_b128 v[184:187], v230 offset:54272
	ds_read_b128 v[188:191], v230 offset:55296
	ds_read_b128 v[192:195], v230 offset:56320
	global_load_lds_dwordx4 v204, s[98:99]
	s_add_i32 m0, s42, 0x2000
	s_add_u32 s34, s34, 0x80080
	s_addc_u32 s35, s35, 0
	s_add_i32 s42, s67, s15
	global_load_lds_dwordx4 v200, s[98:99]
	s_mov_b32 m0, s42
	s_nop 0
	global_load_lds_dwordx4 v204, s[34:35]
	s_add_i32 m0, s42, 0x2000
	s_nop 0
	global_load_lds_dwordx4 v200, s[34:35]
	s_waitcnt vmcnt(6) lgkmcnt(0)
	s_barrier
	v_mfma_f32_16x16x32_bf16 v[64:67], v[132:135], v[164:167], v[64:67]
	v_mfma_f32_16x16x32_bf16 v[64:67], v[136:139], v[168:171], v[64:67]
	v_mfma_f32_16x16x32_bf16 v[56:59], v[132:135], v[172:175], v[56:59]
	v_mfma_f32_16x16x32_bf16 v[56:59], v[136:139], v[176:179], v[56:59]
	v_mfma_f32_16x16x32_bf16 v[48:51], v[132:135], v[180:183], v[48:51]
	v_mfma_f32_16x16x32_bf16 v[48:51], v[136:139], v[184:187], v[48:51]
	v_mfma_f32_16x16x32_bf16 v[40:43], v[132:135], v[188:191], v[40:43]
	v_mfma_f32_16x16x32_bf16 v[40:43], v[136:139], v[192:195], v[40:43]
	v_mfma_f32_16x16x32_bf16 v[60:63], v[140:143], v[164:167], v[60:63]
	v_mfma_f32_16x16x32_bf16 v[60:63], v[144:147], v[168:171], v[60:63]
	v_mfma_f32_16x16x32_bf16 v[52:55], v[140:143], v[172:175], v[52:55]
	v_mfma_f32_16x16x32_bf16 v[52:55], v[144:147], v[176:179], v[52:55]
	v_mfma_f32_16x16x32_bf16 v[44:47], v[140:143], v[180:183], v[44:47]
	v_mfma_f32_16x16x32_bf16 v[44:47], v[144:147], v[184:187], v[44:47]
	v_mfma_f32_16x16x32_bf16 v[36:39], v[140:143], v[188:191], v[36:39]
	v_mfma_f32_16x16x32_bf16 v[36:39], v[144:147], v[192:195], v[36:39]
	v_mfma_f32_16x16x32_bf16 v[32:35], v[148:151], v[164:167], v[32:35]
	v_mfma_f32_16x16x32_bf16 v[32:35], v[152:155], v[168:171], v[32:35]
	v_mfma_f32_16x16x32_bf16 v[28:31], v[156:159], v[164:167], v[28:31]
	v_mfma_f32_16x16x32_bf16 v[28:31], v[160:163], v[168:171], v[28:31]
	v_mfma_f32_16x16x32_bf16 v[24:27], v[148:151], v[172:175], v[24:27]
	v_mfma_f32_16x16x32_bf16 v[24:27], v[152:155], v[176:179], v[24:27]
	v_mfma_f32_16x16x32_bf16 v[20:23], v[156:159], v[172:175], v[20:23]
	v_mfma_f32_16x16x32_bf16 v[20:23], v[160:163], v[176:179], v[20:23]
	v_mfma_f32_16x16x32_bf16 v[16:19], v[148:151], v[180:183], v[16:19]
	v_mfma_f32_16x16x32_bf16 v[16:19], v[152:155], v[184:187], v[16:19]
	v_mfma_f32_16x16x32_bf16 v[12:15], v[156:159], v[180:183], v[12:15]
	v_mfma_f32_16x16x32_bf16 v[12:15], v[160:163], v[184:187], v[12:15]
	v_mfma_f32_16x16x32_bf16 v[6:9], v[148:151], v[188:191], v[8:11]
	v_mfma_f32_16x16x32_bf16 v[8:11], v[152:155], v[192:195], v[6:9]
	v_mfma_f32_16x16x32_bf16 v[2:5], v[156:159], v[188:191], v[2:5]
	v_mfma_f32_16x16x32_bf16 v[4:7], v[160:163], v[192:195], v[2:5]
	s_barrier
	s_add_i32 s57, s57, 2
	s_add_u32 s30, s30, 0x100
	s_addc_u32 s31, s31, 0
	s_add_u32 s55, s55, 0x100
	s_addc_u32 s56, s56, 0
	s_cmp_gt_u32 s57, 29
	s_cbranch_scc0 .LBB0_577
	s_and_b64 vcc, exec, s[20:21]
	s_cbranch_vccz .LBB0_580
	s_barrier

.Lrb_skip_779:
.LBB0_779:
	s_add_u32 s98, s30, 0xfff80000
	s_addc_u32 s99, s31, -1
	s_add_u32 s34, s30, 0xfff80080
	s_addc_u32 s35, s31, -1
	s_add_i32 s66, 0, 0x10000
	s_cmp_eq_u32 s57, 28
	s_cselect_b32 s43, s25, s35
	s_cselect_b32 s42, s53, s34
	s_cselect_b32 s35, s23, s56
	s_cselect_b32 s34, s54, s55
	s_add_i32 s73, 0, 0x14000
	v_add_u32_e32 v114, s66, v157
	v_add_u32_e32 v156, s73, v157
	ds_read_b128 v[90:93], v114
	ds_read_b128 v[94:97], v114 offset:1024
	ds_read_b128 v[106:109], v114 offset:2048
	ds_read_b128 v[114:117], v114 offset:3072
	ds_read_b128 v[162:165], v156
	ds_read_b128 v[166:169], v156 offset:1024
	ds_read_b128 v[170:173], v156 offset:2048
	ds_read_b128 v[174:177], v156 offset:3072
	s_mov_b32 m0, s50
	ds_read_b128 v[178:181], v161
	ds_read_b128 v[182:185], v161 offset:1024
	ds_read_b128 v[186:189], v161 offset:2048
	ds_read_b128 v[190:193], v161 offset:3072
	ds_read_b128 v[200:203], v161 offset:4096
	ds_read_b128 v[204:207], v161 offset:5120
	ds_read_b128 v[208:211], v161 offset:6144
	ds_read_b128 v[212:215], v161 offset:7168
	global_load_lds_dwordx4 v150, s[98:99]
	s_mov_b32 m0, s51
	s_nop 0
	global_load_lds_dwordx4 v148, s[98:99]
	s_add_i32 m0, s14, 0xc000
	s_nop 0
	global_load_lds_dwordx4 v152, s[30:31]
	s_add_i32 m0, s14, 0xe000
	s_nop 0
	global_load_lds_dwordx4 v154, s[30:31]
	s_waitcnt vmcnt(8) lgkmcnt(0)
	s_barrier
	v_mfma_i32_16x16x64_i8 v[142:145], v[90:93], v[178:181], v[142:145]
	v_mfma_i32_16x16x64_i8 v[142:145], v[94:97], v[182:185], v[142:145]
	v_mfma_i32_16x16x64_i8 v[126:129], v[90:93], v[186:189], v[126:129]
	v_mfma_i32_16x16x64_i8 v[126:129], v[94:97], v[190:193], v[126:129]
	v_mfma_i32_16x16x64_i8 v[102:105], v[90:93], v[200:203], v[102:105]
	v_mfma_i32_16x16x64_i8 v[102:105], v[94:97], v[204:207], v[102:105]
	v_mfma_i32_16x16x64_i8 v[78:81], v[90:93], v[208:211], v[78:81]
	v_mfma_i32_16x16x64_i8 v[78:81], v[94:97], v[212:215], v[78:81]
	v_mfma_i32_16x16x64_i8 v[138:141], v[106:109], v[178:181], v[138:141]
	v_mfma_i32_16x16x64_i8 v[138:141], v[114:117], v[182:185], v[138:141]
	v_mfma_i32_16x16x64_i8 v[122:125], v[106:109], v[186:189], v[122:125]
	v_mfma_i32_16x16x64_i8 v[122:125], v[114:117], v[190:193], v[122:125]
	v_mfma_i32_16x16x64_i8 v[98:101], v[106:109], v[200:203], v[98:101]
	v_mfma_i32_16x16x64_i8 v[98:101], v[114:117], v[204:207], v[98:101]
	v_mfma_i32_16x16x64_i8 v[74:77], v[106:109], v[208:211], v[74:77]
	v_mfma_i32_16x16x64_i8 v[74:77], v[114:117], v[212:215], v[74:77]
	v_mfma_i32_16x16x64_i8 v[134:137], v[162:165], v[178:181], v[134:137]
	v_mfma_i32_16x16x64_i8 v[134:137], v[166:169], v[182:185], v[134:137]
	v_mfma_i32_16x16x64_i8 v[118:121], v[162:165], v[186:189], v[118:121]
	v_mfma_i32_16x16x64_i8 v[118:121], v[166:169], v[190:193], v[118:121]
	v_mfma_i32_16x16x64_i8 v[86:89], v[162:165], v[200:203], v[86:89]
	v_mfma_i32_16x16x64_i8 v[86:89], v[166:169], v[204:207], v[86:89]
	v_mfma_i32_16x16x64_i8 v[70:73], v[162:165], v[208:211], v[70:73]
	v_mfma_i32_16x16x64_i8 v[70:73], v[166:169], v[212:215], v[70:73]
	v_mfma_i32_16x16x64_i8 v[130:133], v[170:173], v[178:181], v[130:133]
	v_mfma_i32_16x16x64_i8 v[130:133], v[174:177], v[182:185], v[130:133]
	v_mfma_i32_16x16x64_i8 v[110:113], v[170:173], v[186:189], v[110:113]
	v_mfma_i32_16x16x64_i8 v[110:113], v[174:177], v[190:193], v[110:113]
	v_mfma_i32_16x16x64_i8 v[82:85], v[170:173], v[200:203], v[82:85]
	v_mfma_i32_16x16x64_i8 v[82:85], v[174:177], v[204:207], v[82:85]
	v_mfma_i32_16x16x64_i8 v[66:69], v[170:173], v[208:211], v[66:69]
	v_mfma_i32_16x16x64_i8 v[66:69], v[174:177], v[212:215], v[66:69]
	s_barrier
	s_add_i32 s66, s66, s9
	s_mov_b32 m0, s66
	ds_read_b128 v[178:181], v161 offset:16384
	ds_read_b128 v[182:185], v161 offset:17408
	ds_read_b128 v[186:189], v161 offset:18432
	ds_read_b128 v[190:193], v161 offset:19456
	ds_read_b128 v[200:203], v161 offset:20480
	ds_read_b128 v[204:207], v161 offset:21504
	ds_read_b128 v[208:211], v161 offset:22528
	ds_read_b128 v[212:215], v161 offset:23552
	global_load_lds_dwordx4 v0, s[34:35]
	s_add_i32 m0, s66, 0x2000
	s_add_u32 s66, s34, 0x80000
	s_addc_u32 s67, s35, 0
	s_add_i32 s73, s73, s9
	global_load_lds_dwordx4 v146, s[34:35]
	s_mov_b32 m0, s73
	s_nop 0
	global_load_lds_dwordx4 v0, s[66:67]
	s_add_i32 m0, s73, 0x2000
	s_nop 0
	global_load_lds_dwordx4 v146, s[66:67]
	s_waitcnt vmcnt(6) lgkmcnt(0)
	s_barrier
	v_mfma_i32_16x16x64_i8 v[62:65], v[90:93], v[178:181], v[62:65]
	v_mfma_i32_16x16x64_i8 v[62:65], v[94:97], v[182:185], v[62:65]
	v_mfma_i32_16x16x64_i8 v[46:49], v[90:93], v[186:189], v[46:49]
	v_mfma_i32_16x16x64_i8 v[46:49], v[94:97], v[190:193], v[46:49]
	v_mfma_i32_16x16x64_i8 v[30:33], v[90:93], v[200:203], v[30:33]
	v_mfma_i32_16x16x64_i8 v[30:33], v[94:97], v[204:207], v[30:33]
	v_mfma_i32_16x16x64_i8 v[14:17], v[90:93], v[208:211], v[14:17]
	v_mfma_i32_16x16x64_i8 v[14:17], v[94:97], v[212:215], v[14:17]
	v_mfma_i32_16x16x64_i8 v[58:61], v[106:109], v[178:181], v[58:61]
	v_mfma_i32_16x16x64_i8 v[58:61], v[114:117], v[182:185], v[58:61]
	v_mfma_i32_16x16x64_i8 v[42:45], v[106:109], v[186:189], v[42:45]
	v_mfma_i32_16x16x64_i8 v[42:45], v[114:117], v[190:193], v[42:45]
	v_mfma_i32_16x16x64_i8 v[26:29], v[106:109], v[200:203], v[26:29]
	v_mfma_i32_16x16x64_i8 v[26:29], v[114:117], v[204:207], v[26:29]
	v_mfma_i32_16x16x64_i8 v[10:13], v[106:109], v[208:211], v[10:13]
	v_mfma_i32_16x16x64_i8 v[10:13], v[114:117], v[212:215], v[10:13]
	v_mfma_i32_16x16x64_i8 v[54:57], v[162:165], v[178:181], v[54:57]
	v_mfma_i32_16x16x64_i8 v[54:57], v[166:169], v[182:185], v[54:57]
	v_mfma_i32_16x16x64_i8 v[38:41], v[162:165], v[186:189], v[38:41]
	v_mfma_i32_16x16x64_i8 v[38:41], v[166:169], v[190:193], v[38:41]
	v_mfma_i32_16x16x64_i8 v[22:25], v[162:165], v[200:203], v[22:25]
	v_mfma_i32_16x16x64_i8 v[22:25], v[166:169], v[204:207], v[22:25]
	v_mfma_i32_16x16x64_i8 v[6:9], v[162:165], v[208:211], v[6:9]
	v_mfma_i32_16x16x64_i8 v[6:9], v[166:169], v[212:215], v[6:9]
	v_mfma_i32_16x16x64_i8 v[50:53], v[170:173], v[178:181], v[50:53]
	v_mfma_i32_16x16x64_i8 v[50:53], v[174:177], v[182:185], v[50:53]
	v_mfma_i32_16x16x64_i8 v[34:37], v[170:173], v[186:189], v[34:37]
	v_mfma_i32_16x16x64_i8 v[34:37], v[174:177], v[190:193], v[34:37]
	v_mfma_i32_16x16x64_i8 v[18:21], v[170:173], v[200:203], v[18:21]
	v_mfma_i32_16x16x64_i8 v[18:21], v[174:177], v[204:207], v[18:21]
	v_mfma_i32_16x16x64_i8 v[2:5], v[170:173], v[208:211], v[2:5]
	v_mfma_i32_16x16x64_i8 v[2:5], v[174:177], v[212:215], v[2:5]
	s_barrier
	s_add_i32 s66, 0, 0x18000
	s_add_i32 s67, 0, 0x1c000
	v_add_u32_e32 v114, s66, v157
	v_add_u32_e32 v156, s67, v157
	ds_read_b128 v[90:93], v114
	ds_read_b128 v[94:97], v114 offset:1024
	ds_read_b128 v[106:109], v114 offset:2048
	ds_read_b128 v[114:117], v114 offset:3072
	ds_read_b128 v[162:165], v156
	ds_read_b128 v[166:169], v156 offset:1024
	ds_read_b128 v[170:173], v156 offset:2048
	ds_read_b128 v[174:177], v156 offset:3072
	s_mov_b32 m0, s14
	ds_read_b128 v[178:181], v161 offset:32768
	ds_read_b128 v[182:185], v161 offset:33792
	ds_read_b128 v[186:189], v161 offset:34816
	ds_read_b128 v[190:193], v161 offset:35840
	ds_read_b128 v[200:203], v161 offset:36864
	ds_read_b128 v[204:207], v161 offset:37888
	ds_read_b128 v[208:211], v161 offset:38912
	ds_read_b128 v[212:215], v161 offset:39936
	global_load_lds_dwordx4 v150, s[42:43]
	s_mov_b32 m0, s15
	s_nop 0
	global_load_lds_dwordx4 v148, s[42:43]
	s_add_u32 s42, s42, 0x80000
	s_addc_u32 s43, s43, 0
	s_mov_b32 m0, s46
	s_nop 0
	global_load_lds_dwordx4 v150, s[42:43]
	s_mov_b32 m0, s47
	s_nop 0
	global_load_lds_dwordx4 v148, s[42:43]
	s_waitcnt vmcnt(8) lgkmcnt(0)
	s_barrier
	v_mfma_i32_16x16x64_i8 v[142:145], v[90:93], v[178:181], v[142:145]
	v_mfma_i32_16x16x64_i8 v[142:145], v[94:97], v[182:185], v[142:145]
	v_mfma_i32_16x16x64_i8 v[126:129], v[90:93], v[186:189], v[126:129]
	v_mfma_i32_16x16x64_i8 v[126:129], v[94:97], v[190:193], v[126:129]
	v_mfma_i32_16x16x64_i8 v[102:105], v[90:93], v[200:203], v[102:105]
	v_mfma_i32_16x16x64_i8 v[102:105], v[94:97], v[204:207], v[102:105]
	v_mfma_i32_16x16x64_i8 v[78:81], v[90:93], v[208:211], v[78:81]
	v_mfma_i32_16x16x64_i8 v[78:81], v[94:97], v[212:215], v[78:81]
	v_mfma_i32_16x16x64_i8 v[138:141], v[106:109], v[178:181], v[138:141]
	v_mfma_i32_16x16x64_i8 v[138:141], v[114:117], v[182:185], v[138:141]
	v_mfma_i32_16x16x64_i8 v[122:125], v[106:109], v[186:189], v[122:125]
	v_mfma_i32_16x16x64_i8 v[122:125], v[114:117], v[190:193], v[122:125]
	v_mfma_i32_16x16x64_i8 v[98:101], v[106:109], v[200:203], v[98:101]
	v_mfma_i32_16x16x64_i8 v[98:101], v[114:117], v[204:207], v[98:101]
	v_mfma_i32_16x16x64_i8 v[74:77], v[106:109], v[208:211], v[74:77]
	v_mfma_i32_16x16x64_i8 v[74:77], v[114:117], v[212:215], v[74:77]
	v_mfma_i32_16x16x64_i8 v[134:137], v[162:165], v[178:181], v[134:137]
	v_mfma_i32_16x16x64_i8 v[134:137], v[166:169], v[182:185], v[134:137]
	v_mfma_i32_16x16x64_i8 v[118:121], v[162:165], v[186:189], v[118:121]
	v_mfma_i32_16x16x64_i8 v[118:121], v[166:169], v[190:193], v[118:121]
	v_mfma_i32_16x16x64_i8 v[86:89], v[162:165], v[200:203], v[86:89]
	v_mfma_i32_16x16x64_i8 v[86:89], v[166:169], v[204:207], v[86:89]
	v_mfma_i32_16x16x64_i8 v[70:73], v[162:165], v[208:211], v[70:73]
	v_mfma_i32_16x16x64_i8 v[70:73], v[166:169], v[212:215], v[70:73]
	v_mfma_i32_16x16x64_i8 v[130:133], v[170:173], v[178:181], v[130:133]
	v_mfma_i32_16x16x64_i8 v[130:133], v[174:177], v[182:185], v[130:133]
	v_mfma_i32_16x16x64_i8 v[110:113], v[170:173], v[186:189], v[110:113]
	v_mfma_i32_16x16x64_i8 v[110:113], v[174:177], v[190:193], v[110:113]
	v_mfma_i32_16x16x64_i8 v[82:85], v[170:173], v[200:203], v[82:85]
	v_mfma_i32_16x16x64_i8 v[82:85], v[174:177], v[204:207], v[82:85]
	v_mfma_i32_16x16x64_i8 v[66:69], v[170:173], v[208:211], v[66:69]
	v_mfma_i32_16x16x64_i8 v[66:69], v[174:177], v[212:215], v[66:69]
	s_barrier
	s_add_u32 s98, s34, 0x80
	s_addc_u32 s99, s35, 0
	s_add_i32 s42, s66, s9
	s_mov_b32 m0, s42
	ds_read_b128 v[178:181], v161 offset:49152
	ds_read_b128 v[182:185], v161 offset:50176
	ds_read_b128 v[186:189], v161 offset:51200
	ds_read_b128 v[190:193], v161 offset:52224
	ds_read_b128 v[200:203], v161 offset:53248
	ds_read_b128 v[204:207], v161 offset:54272
	ds_read_b128 v[208:211], v161 offset:55296
	ds_read_b128 v[212:215], v161 offset:56320
	global_load_lds_dwordx4 v0, s[98:99]
	s_add_i32 m0, s42, 0x2000
	s_add_u32 s34, s34, 0x80080
	s_addc_u32 s35, s35, 0
	s_add_i32 s42, s67, s9
	global_load_lds_dwordx4 v146, s[98:99]
	s_mov_b32 m0, s42
	s_nop 0
	global_load_lds_dwordx4 v0, s[34:35]
	s_add_i32 m0, s42, 0x2000
	s_nop 0
	global_load_lds_dwordx4 v146, s[34:35]
	s_waitcnt vmcnt(6) lgkmcnt(0)
	s_barrier
	v_mfma_i32_16x16x64_i8 v[62:65], v[90:93], v[178:181], v[62:65]
	v_mfma_i32_16x16x64_i8 v[62:65], v[94:97], v[182:185], v[62:65]
	v_mfma_i32_16x16x64_i8 v[46:49], v[90:93], v[186:189], v[46:49]
	v_mfma_i32_16x16x64_i8 v[46:49], v[94:97], v[190:193], v[46:49]
	v_mfma_i32_16x16x64_i8 v[30:33], v[90:93], v[200:203], v[30:33]
	v_mfma_i32_16x16x64_i8 v[30:33], v[94:97], v[204:207], v[30:33]
	v_mfma_i32_16x16x64_i8 v[14:17], v[90:93], v[208:211], v[14:17]
	v_mfma_i32_16x16x64_i8 v[14:17], v[94:97], v[212:215], v[14:17]
	v_mfma_i32_16x16x64_i8 v[58:61], v[106:109], v[178:181], v[58:61]
	v_mfma_i32_16x16x64_i8 v[58:61], v[114:117], v[182:185], v[58:61]
	v_mfma_i32_16x16x64_i8 v[42:45], v[106:109], v[186:189], v[42:45]
	v_mfma_i32_16x16x64_i8 v[42:45], v[114:117], v[190:193], v[42:45]
	v_mfma_i32_16x16x64_i8 v[26:29], v[106:109], v[200:203], v[26:29]
	v_mfma_i32_16x16x64_i8 v[26:29], v[114:117], v[204:207], v[26:29]
	v_mfma_i32_16x16x64_i8 v[10:13], v[106:109], v[208:211], v[10:13]
	v_mfma_i32_16x16x64_i8 v[10:13], v[114:117], v[212:215], v[10:13]
	v_mfma_i32_16x16x64_i8 v[54:57], v[162:165], v[178:181], v[54:57]
	v_mfma_i32_16x16x64_i8 v[54:57], v[166:169], v[182:185], v[54:57]
	v_mfma_i32_16x16x64_i8 v[38:41], v[162:165], v[186:189], v[38:41]
	v_mfma_i32_16x16x64_i8 v[38:41], v[166:169], v[190:193], v[38:41]
	v_mfma_i32_16x16x64_i8 v[22:25], v[162:165], v[200:203], v[22:25]
	v_mfma_i32_16x16x64_i8 v[22:25], v[166:169], v[204:207], v[22:25]
	v_mfma_i32_16x16x64_i8 v[6:9], v[162:165], v[208:211], v[6:9]
	v_mfma_i32_16x16x64_i8 v[6:9], v[166:169], v[212:215], v[6:9]
	v_mfma_i32_16x16x64_i8 v[50:53], v[170:173], v[178:181], v[50:53]
	v_mfma_i32_16x16x64_i8 v[50:53], v[174:177], v[182:185], v[50:53]
	v_mfma_i32_16x16x64_i8 v[34:37], v[170:173], v[186:189], v[34:37]
	v_mfma_i32_16x16x64_i8 v[34:37], v[174:177], v[190:193], v[34:37]
	v_mfma_i32_16x16x64_i8 v[18:21], v[170:173], v[200:203], v[18:21]
	v_mfma_i32_16x16x64_i8 v[18:21], v[174:177], v[204:207], v[18:21]
	v_mfma_i32_16x16x64_i8 v[2:5], v[170:173], v[208:211], v[2:5]
	v_mfma_i32_16x16x64_i8 v[2:5], v[174:177], v[212:215], v[2:5]
	s_barrier
	s_add_i32 s57, s57, 2
	s_add_u32 s30, s30, 0x100
	s_addc_u32 s31, s31, 0
	s_add_u32 s55, s55, 0x100
	s_addc_u32 s56, s56, 0
	s_cmp_gt_u32 s57, 29
	s_cbranch_scc0 .LBB0_779
	s_and_b64 vcc, exec, s[20:21]
	s_mov_b32 s54, 0x5c401000
	s_cbranch_vccz .LBB0_782
	s_barrier

.Lrb_skip_801:
.LBB0_801:
	s_add_u32 s98, s30, 0xfff00000
	s_addc_u32 s99, s31, -1
	s_add_u32 s34, s30, 0xfff00080
	s_addc_u32 s35, s31, -1
	s_add_i32 s54, 0, 0x10000
	s_cmp_eq_u32 s53, 60
	s_cselect_b32 s41, s25, s35
	s_cselect_b32 s40, s49, s34
	s_cselect_b32 s35, s23, s52
	s_cselect_b32 s34, s50, s51
	s_add_i32 s56, 0, 0x14000
	v_add_u32_e32 v156, s54, v141
	v_add_u32_e32 v172, s56, v141
	ds_read_b128 v[144:147], v156
	ds_read_b128 v[148:151], v156 offset:1024
	ds_read_b128 v[152:155], v156 offset:2048
	ds_read_b128 v[156:159], v156 offset:3072
	ds_read_b128 v[160:163], v172
	ds_read_b128 v[164:167], v172 offset:1024
	ds_read_b128 v[168:171], v172 offset:2048
	ds_read_b128 v[172:175], v172 offset:3072
	s_mov_b32 m0, s42
	ds_read_b128 v[176:179], v143
	ds_read_b128 v[180:183], v143 offset:1024
	ds_read_b128 v[184:187], v143 offset:2048
	ds_read_b128 v[188:191], v143 offset:3072
	ds_read_b128 v[192:195], v143 offset:4096
	ds_read_b128 v[200:203], v143 offset:5120
	ds_read_b128 v[204:207], v143 offset:6144
	ds_read_b128 v[208:211], v143 offset:7168
	global_load_lds_dwordx4 v134, s[98:99]
	s_mov_b32 m0, s43
	s_nop 0
	global_load_lds_dwordx4 v132, s[98:99]
	s_add_i32 m0, s14, 0xc000
	s_nop 0
	global_load_lds_dwordx4 v136, s[30:31]
	s_add_i32 m0, s14, 0xe000
	s_nop 0
	global_load_lds_dwordx4 v138, s[30:31]
	s_waitcnt vmcnt(8) lgkmcnt(0)
	s_barrier
	v_mfma_f32_16x16x32_bf16 v[126:129], v[144:147], v[176:179], v[126:129]
	v_mfma_f32_16x16x32_bf16 v[126:129], v[148:151], v[180:183], v[126:129]
	v_mfma_f32_16x16x32_bf16 v[118:121], v[144:147], v[184:187], v[118:121]
	v_mfma_f32_16x16x32_bf16 v[118:121], v[148:151], v[188:191], v[118:121]
	v_mfma_f32_16x16x32_bf16 v[102:105], v[144:147], v[192:195], v[102:105]
	v_mfma_f32_16x16x32_bf16 v[102:105], v[148:151], v[200:203], v[102:105]
	v_mfma_f32_16x16x32_bf16 v[86:89], v[144:147], v[204:207], v[86:89]
	v_mfma_f32_16x16x32_bf16 v[86:89], v[148:151], v[208:211], v[86:89]
	v_mfma_f32_16x16x32_bf16 v[122:125], v[152:155], v[176:179], v[122:125]
	v_mfma_f32_16x16x32_bf16 v[122:125], v[156:159], v[180:183], v[122:125]
	v_mfma_f32_16x16x32_bf16 v[114:117], v[152:155], v[184:187], v[114:117]
	v_mfma_f32_16x16x32_bf16 v[114:117], v[156:159], v[188:191], v[114:117]
	v_mfma_f32_16x16x32_bf16 v[98:101], v[152:155], v[192:195], v[98:101]
	v_mfma_f32_16x16x32_bf16 v[98:101], v[156:159], v[200:203], v[98:101]
	v_mfma_f32_16x16x32_bf16 v[82:85], v[152:155], v[204:207], v[82:85]
	v_mfma_f32_16x16x32_bf16 v[82:85], v[156:159], v[208:211], v[82:85]
	v_mfma_f32_16x16x32_bf16 v[110:113], v[160:163], v[176:179], v[110:113]
	v_mfma_f32_16x16x32_bf16 v[110:113], v[164:167], v[180:183], v[110:113]
	v_mfma_f32_16x16x32_bf16 v[94:97], v[160:163], v[184:187], v[94:97]
	v_mfma_f32_16x16x32_bf16 v[94:97], v[164:167], v[188:191], v[94:97]
	v_mfma_f32_16x16x32_bf16 v[78:81], v[160:163], v[192:195], v[78:81]
	v_mfma_f32_16x16x32_bf16 v[78:81], v[164:167], v[200:203], v[78:81]
	v_mfma_f32_16x16x32_bf16 v[70:73], v[160:163], v[204:207], v[70:73]
	v_mfma_f32_16x16x32_bf16 v[70:73], v[164:167], v[208:211], v[70:73]
	v_mfma_f32_16x16x32_bf16 v[106:109], v[168:171], v[176:179], v[106:109]
	v_mfma_f32_16x16x32_bf16 v[106:109], v[172:175], v[180:183], v[106:109]
	v_mfma_f32_16x16x32_bf16 v[90:93], v[168:171], v[184:187], v[90:93]
	v_mfma_f32_16x16x32_bf16 v[90:93], v[172:175], v[188:191], v[90:93]
	v_mfma_f32_16x16x32_bf16 v[74:77], v[168:171], v[192:195], v[74:77]
	v_mfma_f32_16x16x32_bf16 v[74:77], v[172:175], v[200:203], v[74:77]
	v_mfma_f32_16x16x32_bf16 v[66:69], v[168:171], v[204:207], v[66:69]
	v_mfma_f32_16x16x32_bf16 v[66:69], v[172:175], v[208:211], v[66:69]
	s_barrier
	s_add_i32 s54, s54, s9
	s_mov_b32 m0, s54
	ds_read_b128 v[176:179], v143 offset:16384
	ds_read_b128 v[180:183], v143 offset:17408
	ds_read_b128 v[184:187], v143 offset:18432
	ds_read_b128 v[188:191], v143 offset:19456
	ds_read_b128 v[192:195], v143 offset:20480
	ds_read_b128 v[200:203], v143 offset:21504
	ds_read_b128 v[204:207], v143 offset:22528
	ds_read_b128 v[208:211], v143 offset:23552
	global_load_lds_dwordx4 v0, s[34:35]
	s_add_i32 m0, s54, 0x2000
	s_add_u32 s54, s34, 0x100000
	s_addc_u32 s55, s35, 0
	s_add_i32 s56, s56, s9
	global_load_lds_dwordx4 v130, s[34:35]
	s_mov_b32 m0, s56
	s_nop 0
	global_load_lds_dwordx4 v0, s[54:55]
	s_add_i32 m0, s56, 0x2000
	s_nop 0
	global_load_lds_dwordx4 v130, s[54:55]
	s_waitcnt vmcnt(6) lgkmcnt(0)
	s_barrier
	v_mfma_f32_16x16x32_bf16 v[62:65], v[144:147], v[176:179], v[62:65]
	v_mfma_f32_16x16x32_bf16 v[62:65], v[148:151], v[180:183], v[62:65]
	v_mfma_f32_16x16x32_bf16 v[54:57], v[144:147], v[184:187], v[54:57]
	v_mfma_f32_16x16x32_bf16 v[54:57], v[148:151], v[188:191], v[54:57]
	v_mfma_f32_16x16x32_bf16 v[38:41], v[144:147], v[192:195], v[38:41]
	v_mfma_f32_16x16x32_bf16 v[38:41], v[148:151], v[200:203], v[38:41]
	v_mfma_f32_16x16x32_bf16 v[22:25], v[144:147], v[204:207], v[22:25]
	v_mfma_f32_16x16x32_bf16 v[22:25], v[148:151], v[208:211], v[22:25]
	v_mfma_f32_16x16x32_bf16 v[58:61], v[152:155], v[176:179], v[58:61]
	v_mfma_f32_16x16x32_bf16 v[58:61], v[156:159], v[180:183], v[58:61]
	v_mfma_f32_16x16x32_bf16 v[50:53], v[152:155], v[184:187], v[50:53]
	v_mfma_f32_16x16x32_bf16 v[50:53], v[156:159], v[188:191], v[50:53]
	v_mfma_f32_16x16x32_bf16 v[34:37], v[152:155], v[192:195], v[34:37]
	v_mfma_f32_16x16x32_bf16 v[34:37], v[156:159], v[200:203], v[34:37]
	v_mfma_f32_16x16x32_bf16 v[18:21], v[152:155], v[204:207], v[18:21]
	v_mfma_f32_16x16x32_bf16 v[18:21], v[156:159], v[208:211], v[18:21]
	v_mfma_f32_16x16x32_bf16 v[46:49], v[160:163], v[176:179], v[46:49]
	v_mfma_f32_16x16x32_bf16 v[46:49], v[164:167], v[180:183], v[46:49]
	v_mfma_f32_16x16x32_bf16 v[30:33], v[160:163], v[184:187], v[30:33]
	v_mfma_f32_16x16x32_bf16 v[30:33], v[164:167], v[188:191], v[30:33]
	v_mfma_f32_16x16x32_bf16 v[14:17], v[160:163], v[192:195], v[14:17]
	v_mfma_f32_16x16x32_bf16 v[14:17], v[164:167], v[200:203], v[14:17]
	v_mfma_f32_16x16x32_bf16 v[6:9], v[160:163], v[204:207], v[6:9]
	v_mfma_f32_16x16x32_bf16 v[6:9], v[164:167], v[208:211], v[6:9]
	v_mfma_f32_16x16x32_bf16 v[42:45], v[168:171], v[176:179], v[42:45]
	v_mfma_f32_16x16x32_bf16 v[42:45], v[172:175], v[180:183], v[42:45]
	v_mfma_f32_16x16x32_bf16 v[26:29], v[168:171], v[184:187], v[26:29]
	v_mfma_f32_16x16x32_bf16 v[26:29], v[172:175], v[188:191], v[26:29]
	v_mfma_f32_16x16x32_bf16 v[10:13], v[168:171], v[192:195], v[10:13]
	v_mfma_f32_16x16x32_bf16 v[10:13], v[172:175], v[200:203], v[10:13]
	v_mfma_f32_16x16x32_bf16 v[2:5], v[168:171], v[204:207], v[2:5]
	v_mfma_f32_16x16x32_bf16 v[2:5], v[172:175], v[208:211], v[2:5]
	s_barrier
	s_add_i32 s54, 0, 0x18000
	s_add_i32 s55, 0, 0x1c000
	v_add_u32_e32 v156, s54, v141
	v_add_u32_e32 v172, s55, v141
	ds_read_b128 v[144:147], v156
	ds_read_b128 v[148:151], v156 offset:1024
	ds_read_b128 v[152:155], v156 offset:2048
	ds_read_b128 v[156:159], v156 offset:3072
	ds_read_b128 v[160:163], v172
	ds_read_b128 v[164:167], v172 offset:1024
	ds_read_b128 v[168:171], v172 offset:2048
	ds_read_b128 v[172:175], v172 offset:3072
	s_mov_b32 m0, s14
	ds_read_b128 v[176:179], v143 offset:32768
	ds_read_b128 v[180:183], v143 offset:33792
	ds_read_b128 v[184:187], v143 offset:34816
	ds_read_b128 v[188:191], v143 offset:35840
	ds_read_b128 v[192:195], v143 offset:36864
	ds_read_b128 v[200:203], v143 offset:37888
	ds_read_b128 v[204:207], v143 offset:38912
	ds_read_b128 v[208:211], v143 offset:39936
	global_load_lds_dwordx4 v134, s[40:41]
	s_mov_b32 m0, s15
	s_nop 0
	global_load_lds_dwordx4 v132, s[40:41]
	s_add_u32 s40, s40, 0x100000
	s_addc_u32 s41, s41, 0
	s_mov_b32 m0, s18
	s_nop 0
	global_load_lds_dwordx4 v134, s[40:41]
	s_mov_b32 m0, s19
	s_nop 0
	global_load_lds_dwordx4 v132, s[40:41]
	s_waitcnt vmcnt(8) lgkmcnt(0)
	s_barrier
	v_mfma_f32_16x16x32_bf16 v[126:129], v[144:147], v[176:179], v[126:129]
	v_mfma_f32_16x16x32_bf16 v[126:129], v[148:151], v[180:183], v[126:129]
	v_mfma_f32_16x16x32_bf16 v[118:121], v[144:147], v[184:187], v[118:121]
	v_mfma_f32_16x16x32_bf16 v[118:121], v[148:151], v[188:191], v[118:121]
	v_mfma_f32_16x16x32_bf16 v[102:105], v[144:147], v[192:195], v[102:105]
	v_mfma_f32_16x16x32_bf16 v[102:105], v[148:151], v[200:203], v[102:105]
	v_mfma_f32_16x16x32_bf16 v[86:89], v[144:147], v[204:207], v[86:89]
	v_mfma_f32_16x16x32_bf16 v[86:89], v[148:151], v[208:211], v[86:89]
	v_mfma_f32_16x16x32_bf16 v[122:125], v[152:155], v[176:179], v[122:125]
	v_mfma_f32_16x16x32_bf16 v[122:125], v[156:159], v[180:183], v[122:125]
	v_mfma_f32_16x16x32_bf16 v[114:117], v[152:155], v[184:187], v[114:117]
	v_mfma_f32_16x16x32_bf16 v[114:117], v[156:159], v[188:191], v[114:117]
	v_mfma_f32_16x16x32_bf16 v[98:101], v[152:155], v[192:195], v[98:101]
	v_mfma_f32_16x16x32_bf16 v[98:101], v[156:159], v[200:203], v[98:101]
	v_mfma_f32_16x16x32_bf16 v[82:85], v[152:155], v[204:207], v[82:85]
	v_mfma_f32_16x16x32_bf16 v[82:85], v[156:159], v[208:211], v[82:85]
	v_mfma_f32_16x16x32_bf16 v[110:113], v[160:163], v[176:179], v[110:113]
	v_mfma_f32_16x16x32_bf16 v[110:113], v[164:167], v[180:183], v[110:113]
	v_mfma_f32_16x16x32_bf16 v[94:97], v[160:163], v[184:187], v[94:97]
	v_mfma_f32_16x16x32_bf16 v[94:97], v[164:167], v[188:191], v[94:97]
	v_mfma_f32_16x16x32_bf16 v[78:81], v[160:163], v[192:195], v[78:81]
	v_mfma_f32_16x16x32_bf16 v[78:81], v[164:167], v[200:203], v[78:81]
	v_mfma_f32_16x16x32_bf16 v[70:73], v[160:163], v[204:207], v[70:73]
	v_mfma_f32_16x16x32_bf16 v[70:73], v[164:167], v[208:211], v[70:73]
	v_mfma_f32_16x16x32_bf16 v[106:109], v[168:171], v[176:179], v[106:109]
	v_mfma_f32_16x16x32_bf16 v[106:109], v[172:175], v[180:183], v[106:109]
	v_mfma_f32_16x16x32_bf16 v[90:93], v[168:171], v[184:187], v[90:93]
	v_mfma_f32_16x16x32_bf16 v[90:93], v[172:175], v[188:191], v[90:93]
	v_mfma_f32_16x16x32_bf16 v[74:77], v[168:171], v[192:195], v[74:77]
	v_mfma_f32_16x16x32_bf16 v[74:77], v[172:175], v[200:203], v[74:77]
	v_mfma_f32_16x16x32_bf16 v[66:69], v[168:171], v[204:207], v[66:69]
	v_mfma_f32_16x16x32_bf16 v[66:69], v[172:175], v[208:211], v[66:69]
	s_barrier
	s_add_u32 s98, s34, 0x80
	s_addc_u32 s99, s35, 0
	s_add_i32 s40, s54, s9
	s_mov_b32 m0, s40
	ds_read_b128 v[176:179], v143 offset:49152
	ds_read_b128 v[180:183], v143 offset:50176
	ds_read_b128 v[184:187], v143 offset:51200
	ds_read_b128 v[188:191], v143 offset:52224
	ds_read_b128 v[192:195], v143 offset:53248
	ds_read_b128 v[200:203], v143 offset:54272
	ds_read_b128 v[204:207], v143 offset:55296
	ds_read_b128 v[208:211], v143 offset:56320
	global_load_lds_dwordx4 v0, s[98:99]
	s_add_i32 m0, s40, 0x2000
	s_add_u32 s34, s34, 0x100080
	s_addc_u32 s35, s35, 0
	s_add_i32 s40, s55, s9
	global_load_lds_dwordx4 v130, s[98:99]
	s_mov_b32 m0, s40
	s_nop 0
	global_load_lds_dwordx4 v0, s[34:35]
	s_add_i32 m0, s40, 0x2000
	s_nop 0
	global_load_lds_dwordx4 v130, s[34:35]
	s_waitcnt vmcnt(6) lgkmcnt(0)
	s_barrier
	v_mfma_f32_16x16x32_bf16 v[62:65], v[144:147], v[176:179], v[62:65]
	v_mfma_f32_16x16x32_bf16 v[62:65], v[148:151], v[180:183], v[62:65]
	v_mfma_f32_16x16x32_bf16 v[54:57], v[144:147], v[184:187], v[54:57]
	v_mfma_f32_16x16x32_bf16 v[54:57], v[148:151], v[188:191], v[54:57]
	v_mfma_f32_16x16x32_bf16 v[38:41], v[144:147], v[192:195], v[38:41]
	v_mfma_f32_16x16x32_bf16 v[38:41], v[148:151], v[200:203], v[38:41]
	v_mfma_f32_16x16x32_bf16 v[22:25], v[144:147], v[204:207], v[22:25]
	v_mfma_f32_16x16x32_bf16 v[22:25], v[148:151], v[208:211], v[22:25]
	v_mfma_f32_16x16x32_bf16 v[58:61], v[152:155], v[176:179], v[58:61]
	v_mfma_f32_16x16x32_bf16 v[58:61], v[156:159], v[180:183], v[58:61]
	v_mfma_f32_16x16x32_bf16 v[50:53], v[152:155], v[184:187], v[50:53]
	v_mfma_f32_16x16x32_bf16 v[50:53], v[156:159], v[188:191], v[50:53]
	v_mfma_f32_16x16x32_bf16 v[34:37], v[152:155], v[192:195], v[34:37]
	v_mfma_f32_16x16x32_bf16 v[34:37], v[156:159], v[200:203], v[34:37]
	v_mfma_f32_16x16x32_bf16 v[18:21], v[152:155], v[204:207], v[18:21]
	v_mfma_f32_16x16x32_bf16 v[18:21], v[156:159], v[208:211], v[18:21]
	v_mfma_f32_16x16x32_bf16 v[46:49], v[160:163], v[176:179], v[46:49]
	v_mfma_f32_16x16x32_bf16 v[46:49], v[164:167], v[180:183], v[46:49]
	v_mfma_f32_16x16x32_bf16 v[30:33], v[160:163], v[184:187], v[30:33]
	v_mfma_f32_16x16x32_bf16 v[30:33], v[164:167], v[188:191], v[30:33]
	v_mfma_f32_16x16x32_bf16 v[14:17], v[160:163], v[192:195], v[14:17]
	v_mfma_f32_16x16x32_bf16 v[14:17], v[164:167], v[200:203], v[14:17]
	v_mfma_f32_16x16x32_bf16 v[6:9], v[160:163], v[204:207], v[6:9]
	v_mfma_f32_16x16x32_bf16 v[6:9], v[164:167], v[208:211], v[6:9]
	v_mfma_f32_16x16x32_bf16 v[42:45], v[168:171], v[176:179], v[42:45]
	v_mfma_f32_16x16x32_bf16 v[42:45], v[172:175], v[180:183], v[42:45]
	v_mfma_f32_16x16x32_bf16 v[26:29], v[168:171], v[184:187], v[26:29]
	v_mfma_f32_16x16x32_bf16 v[26:29], v[172:175], v[188:191], v[26:29]
	v_mfma_f32_16x16x32_bf16 v[10:13], v[168:171], v[192:195], v[10:13]
	v_mfma_f32_16x16x32_bf16 v[10:13], v[172:175], v[200:203], v[10:13]
	v_mfma_f32_16x16x32_bf16 v[2:5], v[168:171], v[204:207], v[2:5]
	v_mfma_f32_16x16x32_bf16 v[2:5], v[172:175], v[208:211], v[2:5]
	s_barrier
	s_add_i32 s53, s53, 2
	s_add_u32 s30, s30, 0x100
	s_addc_u32 s31, s31, 0
	s_add_u32 s51, s51, 0x100
	s_addc_u32 s52, s52, 0
	s_cmp_gt_u32 s53, 61
	s_cbranch_scc0 .LBB0_801
	s_and_b64 vcc, exec, s[20:21]
	s_cbranch_vccz .LBB0_804
	s_barrier
